# MT=4 K-loops: first K-iteration peeled, its first-touch MFMAs take SrcC=0 so the 128 v_mov accumulator zeroing per unit is gone; plus the earlier setprio/lgkmcnt trims
# baseline (speedup 1.0000x reference)
.LBB0_514:
	s_ashr_i32 s13, s12, 31
	s_lshl_b64 s[14:15], s[12:13], 20
	s_add_u32 s14, s88, s14
	s_addc_u32 s15, s89, s15
	s_and_b64 s[16:17], s[6:7], exec
	s_cselect_b32 s13, s15, s21
	s_cselect_b32 s60, s14, s20
	s_ashr_i32 s11, s10, 31
	s_lshl_b64 s[16:17], s[10:11], 20
	s_add_u32 s16, s24, s16
	s_addc_u32 s17, s25, s17
	s_and_b64 s[22:23], s[6:7], exec
	s_cselect_b32 s11, s17, s19
	s_cselect_b32 s62, s16, s18
	s_add_u32 s64, s20, 0x100
	s_addc_u32 s66, s21, 0
	s_add_u32 s68, s18, 0x100
	s_addc_u32 s70, s19, 0
	s_mov_b32 s72, -2
	v_add_u32_e32 v130, 0x10000, v133
	ds_read_b128 v[136:139], v130
	ds_read_b128 v[140:143], v130 offset:1024
	ds_read_b128 v[144:147], v130 offset:2048
	ds_read_b128 v[148:151], v130 offset:3072
	v_add_u32_e32 v130, 0x14000, v133
	ds_read_b128 v[152:155], v130
	ds_read_b128 v[156:159], v130 offset:1024
	ds_read_b128 v[160:163], v130 offset:2048
	ds_read_b128 v[164:167], v130 offset:3072
	s_cmp_eq_u32 s72, 28
	s_cselect_b32 s18, s60, s64
	s_cselect_b32 s19, s13, s66
	s_cselect_b32 s22, s62, s68
	s_cselect_b32 s23, s11, s70
	s_add_u32 s20, s18, 0x80
	s_addc_u32 s21, s19, 0
	s_add_u32 s74, s64, 0x7ff80
	s_addc_u32 s75, s66, 0
	v_mov_b32_e32 v130, v0
	s_mov_b32 m0, s50
	ds_read_b128 v[168:171], v134
	ds_read_b128 v[172:175], v134 offset:1024
	ds_read_b128 v[176:179], v134 offset:2048
	ds_read_b128 v[180:183], v134 offset:3072
	ds_read_b128 v[184:187], v134 offset:4096
	ds_read_b128 v[188:191], v134 offset:5120
	ds_read_b128 v[192:195], v134 offset:6144
	ds_read_b128 v[196:199], v134 offset:7168
	s_nop 0
	global_load_lds_dwordx4 v130, s[74:75]
	s_add_u32 s74, s64, 0xbff80
	s_addc_u32 s75, s66, 0
	v_mov_b32_e32 v130, v0
	s_mov_b32 m0, s51
	s_nop 0
	global_load_lds_dwordx4 v130, s[74:75]
	s_waitcnt vmcnt(8)
	s_waitcnt lgkmcnt(0)
	s_barrier
	v_mfma_f32_16x16x32_bf16 v[122:125], v[136:139], v[168:171], 0
	v_mfma_f32_16x16x32_bf16 v[114:117], v[144:147], v[168:171], 0
	v_mfma_f32_16x16x32_bf16 v[106:109], v[136:139], v[176:179], 0
	v_mfma_f32_16x16x32_bf16 v[98:101], v[144:147], v[176:179], 0
	v_mfma_f32_16x16x32_bf16 v[90:93], v[136:139], v[184:187], 0
	v_mfma_f32_16x16x32_bf16 v[82:85], v[144:147], v[184:187], 0
	v_mfma_f32_16x16x32_bf16 v[74:77], v[136:139], v[192:195], 0
	v_mfma_f32_16x16x32_bf16 v[66:69], v[144:147], v[192:195], 0
	v_mfma_f32_16x16x32_bf16 v[122:125], v[140:143], v[172:175], v[122:125]
	v_mfma_f32_16x16x32_bf16 v[114:117], v[148:151], v[172:175], v[114:117]
	v_mfma_f32_16x16x32_bf16 v[106:109], v[140:143], v[180:183], v[106:109]
	v_mfma_f32_16x16x32_bf16 v[98:101], v[148:151], v[180:183], v[98:101]
	v_mfma_f32_16x16x32_bf16 v[90:93], v[140:143], v[188:191], v[90:93]
	v_mfma_f32_16x16x32_bf16 v[82:85], v[148:151], v[188:191], v[82:85]
	v_mfma_f32_16x16x32_bf16 v[74:77], v[140:143], v[196:199], v[74:77]
	v_mfma_f32_16x16x32_bf16 v[66:69], v[148:151], v[196:199], v[66:69]
	v_mfma_f32_16x16x32_bf16 v[126:129], v[152:155], v[168:171], 0
	v_mfma_f32_16x16x32_bf16 v[118:121], v[160:163], v[168:171], 0
	v_mfma_f32_16x16x32_bf16 v[110:113], v[152:155], v[176:179], 0
	v_mfma_f32_16x16x32_bf16 v[102:105], v[160:163], v[176:179], 0
	v_mfma_f32_16x16x32_bf16 v[94:97], v[152:155], v[184:187], 0
	v_mfma_f32_16x16x32_bf16 v[86:89], v[160:163], v[184:187], 0
	v_mfma_f32_16x16x32_bf16 v[78:81], v[152:155], v[192:195], 0
	v_mfma_f32_16x16x32_bf16 v[70:73], v[160:163], v[192:195], 0
	v_mfma_f32_16x16x32_bf16 v[126:129], v[156:159], v[172:175], v[126:129]
	v_mfma_f32_16x16x32_bf16 v[118:121], v[164:167], v[172:175], v[118:121]
	v_mfma_f32_16x16x32_bf16 v[110:113], v[156:159], v[180:183], v[110:113]
	v_mfma_f32_16x16x32_bf16 v[102:105], v[164:167], v[180:183], v[102:105]
	v_mfma_f32_16x16x32_bf16 v[94:97], v[156:159], v[188:191], v[94:97]
	v_mfma_f32_16x16x32_bf16 v[86:89], v[164:167], v[188:191], v[86:89]
	v_mfma_f32_16x16x32_bf16 v[78:81], v[156:159], v[196:199], v[78:81]
	v_mfma_f32_16x16x32_bf16 v[70:73], v[164:167], v[196:199], v[70:73]
	s_barrier
	s_mov_b64 s[74:75], s[22:23]
	v_mov_b32_e32 v130, v132
	s_mov_b32 m0, s27
	ds_read_b128 v[168:171], v134 offset:16384
	ds_read_b128 v[172:175], v134 offset:17408
	ds_read_b128 v[176:179], v134 offset:18432
	ds_read_b128 v[180:183], v134 offset:19456
	ds_read_b128 v[184:187], v134 offset:20480
	ds_read_b128 v[188:191], v134 offset:21504
	ds_read_b128 v[192:195], v134 offset:22528
	ds_read_b128 v[196:199], v134 offset:23552
	s_nop 0
	global_load_lds_dwordx4 v130, s[74:75]
	s_add_u32 s74, s22, 0x40000
	s_addc_u32 s75, s23, 0
	v_mov_b32_e32 v130, v132
	s_mov_b32 m0, s28
	s_nop 0
	global_load_lds_dwordx4 v130, s[74:75]
	s_add_u32 s74, s22, 0x80000
	s_addc_u32 s75, s23, 0
	v_mov_b32_e32 v130, v132
	s_mov_b32 m0, s29
	s_nop 0
	global_load_lds_dwordx4 v130, s[74:75]
	s_add_u32 s74, s22, 0xc0000
	s_addc_u32 s75, s23, 0
	v_mov_b32_e32 v130, v132
	s_mov_b32 m0, s30
	s_nop 0
	global_load_lds_dwordx4 v130, s[74:75]
	s_mov_b64 s[74:75], s[18:19]
	v_mov_b32_e32 v130, v0
	s_mov_b32 m0, s26
	s_nop 0
	global_load_lds_dwordx4 v130, s[74:75]
	s_add_u32 s74, s18, 0x40000
	s_addc_u32 s75, s19, 0
	v_mov_b32_e32 v130, v0
	s_mov_b32 m0, s31
	s_nop 0
	global_load_lds_dwordx4 v130, s[74:75]
	s_waitcnt vmcnt(8)
	s_waitcnt lgkmcnt(0)
	s_barrier
	v_mfma_f32_16x16x32_bf16 v[58:61], v[136:139], v[168:171], 0
	v_mfma_f32_16x16x32_bf16 v[50:53], v[144:147], v[168:171], 0
	v_mfma_f32_16x16x32_bf16 v[42:45], v[136:139], v[176:179], 0
	v_mfma_f32_16x16x32_bf16 v[34:37], v[144:147], v[176:179], 0
	v_mfma_f32_16x16x32_bf16 v[26:29], v[136:139], v[184:187], 0
	v_mfma_f32_16x16x32_bf16 v[18:21], v[144:147], v[184:187], 0
	v_mfma_f32_16x16x32_bf16 v[10:13], v[136:139], v[192:195], 0
	v_mfma_f32_16x16x32_bf16 v[2:5], v[144:147], v[192:195], 0
	v_mfma_f32_16x16x32_bf16 v[58:61], v[140:143], v[172:175], v[58:61]
	v_mfma_f32_16x16x32_bf16 v[50:53], v[148:151], v[172:175], v[50:53]
	v_mfma_f32_16x16x32_bf16 v[42:45], v[140:143], v[180:183], v[42:45]
	v_mfma_f32_16x16x32_bf16 v[34:37], v[148:151], v[180:183], v[34:37]
	v_mfma_f32_16x16x32_bf16 v[26:29], v[140:143], v[188:191], v[26:29]
	v_mfma_f32_16x16x32_bf16 v[18:21], v[148:151], v[188:191], v[18:21]
	v_mfma_f32_16x16x32_bf16 v[10:13], v[140:143], v[196:199], v[10:13]
	v_mfma_f32_16x16x32_bf16 v[2:5], v[148:151], v[196:199], v[2:5]
	v_mfma_f32_16x16x32_bf16 v[62:65], v[152:155], v[168:171], 0
	v_mfma_f32_16x16x32_bf16 v[54:57], v[160:163], v[168:171], 0
	v_mfma_f32_16x16x32_bf16 v[46:49], v[152:155], v[176:179], 0
	v_mfma_f32_16x16x32_bf16 v[38:41], v[160:163], v[176:179], 0
	v_mfma_f32_16x16x32_bf16 v[30:33], v[152:155], v[184:187], 0
	v_mfma_f32_16x16x32_bf16 v[22:25], v[160:163], v[184:187], 0
	v_mfma_f32_16x16x32_bf16 v[14:17], v[152:155], v[192:195], 0
	v_mfma_f32_16x16x32_bf16 v[6:9], v[160:163], v[192:195], 0
	v_mfma_f32_16x16x32_bf16 v[62:65], v[156:159], v[172:175], v[62:65]
	v_mfma_f32_16x16x32_bf16 v[54:57], v[164:167], v[172:175], v[54:57]
	v_mfma_f32_16x16x32_bf16 v[46:49], v[156:159], v[180:183], v[46:49]
	v_mfma_f32_16x16x32_bf16 v[38:41], v[164:167], v[180:183], v[38:41]
	v_mfma_f32_16x16x32_bf16 v[30:33], v[156:159], v[188:191], v[30:33]
	v_mfma_f32_16x16x32_bf16 v[22:25], v[164:167], v[188:191], v[22:25]
	v_mfma_f32_16x16x32_bf16 v[14:17], v[156:159], v[196:199], v[14:17]
	v_mfma_f32_16x16x32_bf16 v[6:9], v[164:167], v[196:199], v[6:9]
	s_barrier
	v_add_u32_e32 v130, 0x18000, v133
	ds_read_b128 v[136:139], v130
	ds_read_b128 v[140:143], v130 offset:1024
	ds_read_b128 v[144:147], v130 offset:2048
	ds_read_b128 v[148:151], v130 offset:3072
	v_add_u32_e32 v130, 0x1c000, v133
	ds_read_b128 v[152:155], v130
	ds_read_b128 v[156:159], v130 offset:1024
	ds_read_b128 v[160:163], v130 offset:2048
	ds_read_b128 v[164:167], v130 offset:3072
	s_add_u32 s74, s18, 0x80000
	s_addc_u32 s75, s19, 0
	v_mov_b32_e32 v130, v0
	s_mov_b32 m0, s34
	ds_read_b128 v[168:171], v134 offset:32768
	ds_read_b128 v[172:175], v134 offset:33792
	ds_read_b128 v[176:179], v134 offset:34816
	ds_read_b128 v[180:183], v134 offset:35840
	ds_read_b128 v[184:187], v134 offset:36864
	ds_read_b128 v[188:191], v134 offset:37888
	ds_read_b128 v[192:195], v134 offset:38912
	ds_read_b128 v[196:199], v134 offset:39936
	s_nop 0
	global_load_lds_dwordx4 v130, s[74:75]
	s_add_u32 s74, s18, 0xc0000
	s_addc_u32 s75, s19, 0
	v_mov_b32_e32 v130, v0
	s_mov_b32 m0, s35
	s_nop 0
	global_load_lds_dwordx4 v130, s[74:75]
	s_waitcnt vmcnt(8)
	s_waitcnt lgkmcnt(0)
	s_barrier
	v_mfma_f32_16x16x32_bf16 v[122:125], v[136:139], v[168:171], v[122:125]
	v_mfma_f32_16x16x32_bf16 v[114:117], v[144:147], v[168:171], v[114:117]
	v_mfma_f32_16x16x32_bf16 v[106:109], v[136:139], v[176:179], v[106:109]
	v_mfma_f32_16x16x32_bf16 v[98:101], v[144:147], v[176:179], v[98:101]
	v_mfma_f32_16x16x32_bf16 v[90:93], v[136:139], v[184:187], v[90:93]
	v_mfma_f32_16x16x32_bf16 v[82:85], v[144:147], v[184:187], v[82:85]
	v_mfma_f32_16x16x32_bf16 v[74:77], v[136:139], v[192:195], v[74:77]
	v_mfma_f32_16x16x32_bf16 v[66:69], v[144:147], v[192:195], v[66:69]
	v_mfma_f32_16x16x32_bf16 v[122:125], v[140:143], v[172:175], v[122:125]
	v_mfma_f32_16x16x32_bf16 v[114:117], v[148:151], v[172:175], v[114:117]
	v_mfma_f32_16x16x32_bf16 v[106:109], v[140:143], v[180:183], v[106:109]
	v_mfma_f32_16x16x32_bf16 v[98:101], v[148:151], v[180:183], v[98:101]
	v_mfma_f32_16x16x32_bf16 v[90:93], v[140:143], v[188:191], v[90:93]
	v_mfma_f32_16x16x32_bf16 v[82:85], v[148:151], v[188:191], v[82:85]
	v_mfma_f32_16x16x32_bf16 v[74:77], v[140:143], v[196:199], v[74:77]
	v_mfma_f32_16x16x32_bf16 v[66:69], v[148:151], v[196:199], v[66:69]
	v_mfma_f32_16x16x32_bf16 v[126:129], v[152:155], v[168:171], v[126:129]
	v_mfma_f32_16x16x32_bf16 v[118:121], v[160:163], v[168:171], v[118:121]
	v_mfma_f32_16x16x32_bf16 v[110:113], v[152:155], v[176:179], v[110:113]
	v_mfma_f32_16x16x32_bf16 v[102:105], v[160:163], v[176:179], v[102:105]
	v_mfma_f32_16x16x32_bf16 v[94:97], v[152:155], v[184:187], v[94:97]
	v_mfma_f32_16x16x32_bf16 v[86:89], v[160:163], v[184:187], v[86:89]
	v_mfma_f32_16x16x32_bf16 v[78:81], v[152:155], v[192:195], v[78:81]
	v_mfma_f32_16x16x32_bf16 v[70:73], v[160:163], v[192:195], v[70:73]
	v_mfma_f32_16x16x32_bf16 v[126:129], v[156:159], v[172:175], v[126:129]
	v_mfma_f32_16x16x32_bf16 v[118:121], v[164:167], v[172:175], v[118:121]
	v_mfma_f32_16x16x32_bf16 v[110:113], v[156:159], v[180:183], v[110:113]
	v_mfma_f32_16x16x32_bf16 v[102:105], v[164:167], v[180:183], v[102:105]
	v_mfma_f32_16x16x32_bf16 v[94:97], v[156:159], v[188:191], v[94:97]
	v_mfma_f32_16x16x32_bf16 v[86:89], v[164:167], v[188:191], v[86:89]
	v_mfma_f32_16x16x32_bf16 v[78:81], v[156:159], v[196:199], v[78:81]
	v_mfma_f32_16x16x32_bf16 v[70:73], v[164:167], v[196:199], v[70:73]
	s_barrier
	s_add_u32 s74, s22, 0x80
	s_addc_u32 s75, s23, 0
	v_mov_b32_e32 v130, v132
	s_mov_b32 m0, s38
	ds_read_b128 v[168:171], v134 offset:49152
	ds_read_b128 v[172:175], v134 offset:50176
	ds_read_b128 v[176:179], v134 offset:51200
	ds_read_b128 v[180:183], v134 offset:52224
	ds_read_b128 v[184:187], v134 offset:53248
	ds_read_b128 v[188:191], v134 offset:54272
	ds_read_b128 v[192:195], v134 offset:55296
	ds_read_b128 v[196:199], v134 offset:56320
	s_nop 0
	global_load_lds_dwordx4 v130, s[74:75]
	s_add_u32 s74, s22, 0x40080
	s_addc_u32 s75, s23, 0
	v_mov_b32_e32 v130, v132
	s_mov_b32 m0, s39
	s_nop 0
	global_load_lds_dwordx4 v130, s[74:75]
	s_add_u32 s74, s22, 0x80080
	s_addc_u32 s75, s23, 0
	v_mov_b32_e32 v130, v132
	s_mov_b32 m0, s42
	s_add_u32 s22, s22, 0xc0080
	global_load_lds_dwordx4 v130, s[74:75]
	s_addc_u32 s23, s23, 0
	v_mov_b32_e32 v130, v132
	s_mov_b32 m0, s43
	s_add_u32 s18, s18, 0x40080
	global_load_lds_dwordx4 v130, s[22:23]
	v_mov_b32_e32 v130, v0
	s_mov_b32 m0, s40
	s_addc_u32 s19, s19, 0
	global_load_lds_dwordx4 v130, s[20:21]
	v_mov_b32_e32 v130, v0
	s_mov_b32 m0, s41
	s_nop 0
	global_load_lds_dwordx4 v130, s[18:19]
	s_waitcnt vmcnt(8)
	s_waitcnt lgkmcnt(0)
	s_barrier
	v_mfma_f32_16x16x32_bf16 v[58:61], v[136:139], v[168:171], v[58:61]
	v_mfma_f32_16x16x32_bf16 v[50:53], v[144:147], v[168:171], v[50:53]
	v_mfma_f32_16x16x32_bf16 v[42:45], v[136:139], v[176:179], v[42:45]
	v_mfma_f32_16x16x32_bf16 v[34:37], v[144:147], v[176:179], v[34:37]
	v_mfma_f32_16x16x32_bf16 v[26:29], v[136:139], v[184:187], v[26:29]
	v_mfma_f32_16x16x32_bf16 v[18:21], v[144:147], v[184:187], v[18:21]
	v_mfma_f32_16x16x32_bf16 v[10:13], v[136:139], v[192:195], v[10:13]
	v_mfma_f32_16x16x32_bf16 v[2:5], v[144:147], v[192:195], v[2:5]
	v_mfma_f32_16x16x32_bf16 v[58:61], v[140:143], v[172:175], v[58:61]
	v_mfma_f32_16x16x32_bf16 v[50:53], v[148:151], v[172:175], v[50:53]
	v_mfma_f32_16x16x32_bf16 v[42:45], v[140:143], v[180:183], v[42:45]
	v_mfma_f32_16x16x32_bf16 v[34:37], v[148:151], v[180:183], v[34:37]
	v_mfma_f32_16x16x32_bf16 v[26:29], v[140:143], v[188:191], v[26:29]
	v_mfma_f32_16x16x32_bf16 v[18:21], v[148:151], v[188:191], v[18:21]
	v_mfma_f32_16x16x32_bf16 v[10:13], v[140:143], v[196:199], v[10:13]
	v_mfma_f32_16x16x32_bf16 v[2:5], v[148:151], v[196:199], v[2:5]
	v_mfma_f32_16x16x32_bf16 v[62:65], v[152:155], v[168:171], v[62:65]
	v_mfma_f32_16x16x32_bf16 v[54:57], v[160:163], v[168:171], v[54:57]
	v_mfma_f32_16x16x32_bf16 v[46:49], v[152:155], v[176:179], v[46:49]
	v_mfma_f32_16x16x32_bf16 v[38:41], v[160:163], v[176:179], v[38:41]
	v_mfma_f32_16x16x32_bf16 v[30:33], v[152:155], v[184:187], v[30:33]
	v_mfma_f32_16x16x32_bf16 v[22:25], v[160:163], v[184:187], v[22:25]
	v_mfma_f32_16x16x32_bf16 v[14:17], v[152:155], v[192:195], v[14:17]
	v_mfma_f32_16x16x32_bf16 v[6:9], v[160:163], v[192:195], v[6:9]
	v_mfma_f32_16x16x32_bf16 v[62:65], v[156:159], v[172:175], v[62:65]
	v_mfma_f32_16x16x32_bf16 v[54:57], v[164:167], v[172:175], v[54:57]
	v_mfma_f32_16x16x32_bf16 v[46:49], v[156:159], v[180:183], v[46:49]
	v_mfma_f32_16x16x32_bf16 v[38:41], v[164:167], v[180:183], v[38:41]
	v_mfma_f32_16x16x32_bf16 v[30:33], v[156:159], v[188:191], v[30:33]
	v_mfma_f32_16x16x32_bf16 v[22:25], v[164:167], v[188:191], v[22:25]
	v_mfma_f32_16x16x32_bf16 v[14:17], v[156:159], v[196:199], v[14:17]
	v_mfma_f32_16x16x32_bf16 v[6:9], v[164:167], v[196:199], v[6:9]
	s_barrier
	s_add_i32 s72, s72, 2
	s_add_u32 s64, s64, 0x100
	s_addc_u32 s66, s66, 0
	s_add_u32 s68, s68, 0x100
	s_addc_u32 s70, s70, 0
	s_cmp_gt_u32 s72, 29
	s_cbranch_scc0 .LBB0_515

.LBB0_1045:
	s_ashr_i32 s21, s20, 31
	s_lshl_b64 s[16:17], s[20:21], 20
	s_add_u32 s22, s88, s16
	s_addc_u32 s23, s89, s17
	s_and_b64 s[16:17], s[8:9], exec
	s_cselect_b32 s21, s23, s7
	s_cselect_b32 s60, s22, s6
	s_ashr_i32 s19, s18, 31
	s_lshl_b64 s[16:17], s[18:19], 20
	s_add_u32 s24, s26, s16
	s_addc_u32 s25, s27, s17
	s_and_b64 s[16:17], s[8:9], exec
	s_cselect_b32 s19, s25, s5
	s_cselect_b32 s62, s24, s4
	s_add_u32 s64, s6, 0x100
	s_addc_u32 s66, s7, 0
	s_add_u32 s68, s4, 0x100
	s_addc_u32 s70, s5, 0
	s_mov_b32 s72, -2
	v_add_u32_e32 v0, 0x10000, v134
	ds_read_b128 v[136:139], v0
	ds_read_b128 v[140:143], v0 offset:1024
	ds_read_b128 v[144:147], v0 offset:2048
	ds_read_b128 v[148:151], v0 offset:3072
	v_add_u32_e32 v0, 0x14000, v134
	ds_read_b128 v[152:155], v0
	ds_read_b128 v[156:159], v0 offset:1024
	ds_read_b128 v[160:163], v0 offset:2048
	ds_read_b128 v[164:167], v0 offset:3072
	s_cmp_eq_u32 s72, 28
	s_cselect_b32 s4, s60, s64
	s_cselect_b32 s5, s21, s66
	s_cselect_b32 s16, s62, s68
	s_cselect_b32 s17, s19, s70
	s_add_u32 s6, s4, 0x80
	s_addc_u32 s7, s5, 0
	s_add_u32 s74, s64, 0x7ff80
	s_addc_u32 s75, s66, 0
	v_mov_b32_e32 v0, v132
	ds_read_b128 v[168:171], v135
	ds_read_b128 v[172:175], v135 offset:1024
	ds_read_b128 v[176:179], v135 offset:2048
	ds_read_b128 v[180:183], v135 offset:3072
	ds_read_b128 v[184:187], v135 offset:4096
	ds_read_b128 v[188:191], v135 offset:5120
	ds_read_b128 v[192:195], v135 offset:6144
	ds_read_b128 v[196:199], v135 offset:7168
	s_add_i32 m0, s28, 0xc000
	s_nop 0
	global_load_lds_dwordx4 v0, s[74:75]
	s_add_u32 s74, s64, 0xbff80
	s_addc_u32 s75, s66, 0
	v_mov_b32_e32 v0, v132
	s_add_i32 m0, s28, 0xe000
	s_nop 0
	global_load_lds_dwordx4 v0, s[74:75]
	s_waitcnt vmcnt(8)
	s_waitcnt lgkmcnt(0)
	s_barrier
	v_mfma_f32_16x16x32_bf16 v[126:129], v[136:139], v[168:171], 0
	v_mfma_f32_16x16x32_bf16 v[122:125], v[144:147], v[168:171], 0
	v_mfma_f32_16x16x32_bf16 v[118:121], v[136:139], v[176:179], 0
	v_mfma_f32_16x16x32_bf16 v[114:117], v[144:147], v[176:179], 0
	v_mfma_f32_16x16x32_bf16 v[102:105], v[136:139], v[184:187], 0
	v_mfma_f32_16x16x32_bf16 v[98:101], v[144:147], v[184:187], 0
	v_mfma_f32_16x16x32_bf16 v[86:89], v[136:139], v[192:195], 0
	v_mfma_f32_16x16x32_bf16 v[82:85], v[144:147], v[192:195], 0
	v_mfma_f32_16x16x32_bf16 v[126:129], v[140:143], v[172:175], v[126:129]
	v_mfma_f32_16x16x32_bf16 v[122:125], v[148:151], v[172:175], v[122:125]
	v_mfma_f32_16x16x32_bf16 v[118:121], v[140:143], v[180:183], v[118:121]
	v_mfma_f32_16x16x32_bf16 v[114:117], v[148:151], v[180:183], v[114:117]
	v_mfma_f32_16x16x32_bf16 v[102:105], v[140:143], v[188:191], v[102:105]
	v_mfma_f32_16x16x32_bf16 v[98:101], v[148:151], v[188:191], v[98:101]
	v_mfma_f32_16x16x32_bf16 v[86:89], v[140:143], v[196:199], v[86:89]
	v_mfma_f32_16x16x32_bf16 v[82:85], v[148:151], v[196:199], v[82:85]
	v_mfma_f32_16x16x32_bf16 v[110:113], v[152:155], v[168:171], 0
	v_mfma_f32_16x16x32_bf16 v[106:109], v[160:163], v[168:171], 0
	v_mfma_f32_16x16x32_bf16 v[94:97], v[152:155], v[176:179], 0
	v_mfma_f32_16x16x32_bf16 v[90:93], v[160:163], v[176:179], 0
	v_mfma_f32_16x16x32_bf16 v[78:81], v[152:155], v[184:187], 0
	v_mfma_f32_16x16x32_bf16 v[74:77], v[160:163], v[184:187], 0
	v_mfma_f32_16x16x32_bf16 v[70:73], v[152:155], v[192:195], 0
	v_mfma_f32_16x16x32_bf16 v[66:69], v[160:163], v[192:195], 0
	v_mfma_f32_16x16x32_bf16 v[110:113], v[156:159], v[172:175], v[110:113]
	v_mfma_f32_16x16x32_bf16 v[106:109], v[164:167], v[172:175], v[106:109]
	v_mfma_f32_16x16x32_bf16 v[94:97], v[156:159], v[180:183], v[94:97]
	v_mfma_f32_16x16x32_bf16 v[90:93], v[164:167], v[180:183], v[90:93]
	v_mfma_f32_16x16x32_bf16 v[78:81], v[156:159], v[188:191], v[78:81]
	v_mfma_f32_16x16x32_bf16 v[74:77], v[164:167], v[188:191], v[74:77]
	v_mfma_f32_16x16x32_bf16 v[70:73], v[156:159], v[196:199], v[70:73]
	v_mfma_f32_16x16x32_bf16 v[66:69], v[164:167], v[196:199], v[66:69]
	s_barrier
	s_mov_b64 s[74:75], s[16:17]
	v_mov_b32_e32 v0, v133
	s_mov_b32 m0, s29
	ds_read_b128 v[168:171], v135 offset:16384
	ds_read_b128 v[172:175], v135 offset:17408
	ds_read_b128 v[176:179], v135 offset:18432
	ds_read_b128 v[180:183], v135 offset:19456
	ds_read_b128 v[184:187], v135 offset:20480
	ds_read_b128 v[188:191], v135 offset:21504
	ds_read_b128 v[192:195], v135 offset:22528
	ds_read_b128 v[196:199], v135 offset:23552
	s_nop 0
	global_load_lds_dwordx4 v0, s[74:75]
	s_add_u32 s74, s16, 0x40000
	s_addc_u32 s75, s17, 0
	v_mov_b32_e32 v0, v133
	s_mov_b32 m0, s30
	s_nop 0
	global_load_lds_dwordx4 v0, s[74:75]
	s_add_u32 s74, s16, 0x80000
	s_addc_u32 s75, s17, 0
	v_mov_b32_e32 v0, v133
	s_mov_b32 m0, s31
	s_nop 0
	global_load_lds_dwordx4 v0, s[74:75]
	s_add_u32 s74, s16, 0xc0000
	s_addc_u32 s75, s17, 0
	v_mov_b32_e32 v0, v133
	s_mov_b32 m0, s34
	s_nop 0
	global_load_lds_dwordx4 v0, s[74:75]
	s_mov_b64 s[74:75], s[4:5]
	v_mov_b32_e32 v0, v132
	s_mov_b32 m0, s28
	s_nop 0
	global_load_lds_dwordx4 v0, s[74:75]
	s_add_u32 s74, s4, 0x40000
	s_addc_u32 s75, s5, 0
	v_mov_b32_e32 v0, v132
	s_mov_b32 m0, s35
	s_nop 0
	global_load_lds_dwordx4 v0, s[74:75]
	s_waitcnt vmcnt(8)
	s_waitcnt lgkmcnt(0)
	s_barrier
	v_mfma_f32_16x16x32_bf16 v[62:65], v[136:139], v[168:171], 0
	v_mfma_f32_16x16x32_bf16 v[58:61], v[144:147], v[168:171], 0
	v_mfma_f32_16x16x32_bf16 v[54:57], v[136:139], v[176:179], 0
	v_mfma_f32_16x16x32_bf16 v[50:53], v[144:147], v[176:179], 0
	v_mfma_f32_16x16x32_bf16 v[38:41], v[136:139], v[184:187], 0
	v_mfma_f32_16x16x32_bf16 v[34:37], v[144:147], v[184:187], 0
	v_mfma_f32_16x16x32_bf16 v[22:25], v[136:139], v[192:195], 0
	v_mfma_f32_16x16x32_bf16 v[18:21], v[144:147], v[192:195], 0
	v_mfma_f32_16x16x32_bf16 v[62:65], v[140:143], v[172:175], v[62:65]
	v_mfma_f32_16x16x32_bf16 v[58:61], v[148:151], v[172:175], v[58:61]
	v_mfma_f32_16x16x32_bf16 v[54:57], v[140:143], v[180:183], v[54:57]
	v_mfma_f32_16x16x32_bf16 v[50:53], v[148:151], v[180:183], v[50:53]
	v_mfma_f32_16x16x32_bf16 v[38:41], v[140:143], v[188:191], v[38:41]
	v_mfma_f32_16x16x32_bf16 v[34:37], v[148:151], v[188:191], v[34:37]
	v_mfma_f32_16x16x32_bf16 v[22:25], v[140:143], v[196:199], v[22:25]
	v_mfma_f32_16x16x32_bf16 v[18:21], v[148:151], v[196:199], v[18:21]
	v_mfma_f32_16x16x32_bf16 v[46:49], v[152:155], v[168:171], 0
	v_mfma_f32_16x16x32_bf16 v[42:45], v[160:163], v[168:171], 0
	v_mfma_f32_16x16x32_bf16 v[30:33], v[152:155], v[176:179], 0
	v_mfma_f32_16x16x32_bf16 v[26:29], v[160:163], v[176:179], 0
	v_mfma_f32_16x16x32_bf16 v[14:17], v[152:155], v[184:187], 0
	v_mfma_f32_16x16x32_bf16 v[10:13], v[160:163], v[184:187], 0
	v_mfma_f32_16x16x32_bf16 v[6:9], v[152:155], v[192:195], 0
	v_mfma_f32_16x16x32_bf16 v[2:5], v[160:163], v[192:195], 0
	v_mfma_f32_16x16x32_bf16 v[46:49], v[156:159], v[172:175], v[46:49]
	v_mfma_f32_16x16x32_bf16 v[42:45], v[164:167], v[172:175], v[42:45]
	v_mfma_f32_16x16x32_bf16 v[30:33], v[156:159], v[180:183], v[30:33]
	v_mfma_f32_16x16x32_bf16 v[26:29], v[164:167], v[180:183], v[26:29]
	v_mfma_f32_16x16x32_bf16 v[14:17], v[156:159], v[188:191], v[14:17]
	v_mfma_f32_16x16x32_bf16 v[10:13], v[164:167], v[188:191], v[10:13]
	v_mfma_f32_16x16x32_bf16 v[6:9], v[156:159], v[196:199], v[6:9]
	v_mfma_f32_16x16x32_bf16 v[2:5], v[164:167], v[196:199], v[2:5]
	s_barrier
	v_add_u32_e32 v0, 0x18000, v134
	ds_read_b128 v[136:139], v0
	ds_read_b128 v[140:143], v0 offset:1024
	ds_read_b128 v[144:147], v0 offset:2048
	ds_read_b128 v[148:151], v0 offset:3072
	v_add_u32_e32 v0, 0x1c000, v134
	ds_read_b128 v[152:155], v0
	ds_read_b128 v[156:159], v0 offset:1024
	ds_read_b128 v[160:163], v0 offset:2048
	ds_read_b128 v[164:167], v0 offset:3072
	s_add_u32 s74, s4, 0x80000
	s_addc_u32 s75, s5, 0
	v_mov_b32_e32 v0, v132
	s_mov_b32 m0, s36
	ds_read_b128 v[168:171], v135 offset:32768
	ds_read_b128 v[172:175], v135 offset:33792
	ds_read_b128 v[176:179], v135 offset:34816
	ds_read_b128 v[180:183], v135 offset:35840
	ds_read_b128 v[184:187], v135 offset:36864
	ds_read_b128 v[188:191], v135 offset:37888
	ds_read_b128 v[192:195], v135 offset:38912
	ds_read_b128 v[196:199], v135 offset:39936
	s_nop 0
	global_load_lds_dwordx4 v0, s[74:75]
	s_add_u32 s74, s4, 0xc0000
	s_addc_u32 s75, s5, 0
	v_mov_b32_e32 v0, v132
	s_mov_b32 m0, s37
	s_nop 0
	global_load_lds_dwordx4 v0, s[74:75]
	s_waitcnt vmcnt(8)
	s_waitcnt lgkmcnt(0)
	s_barrier
	v_mfma_f32_16x16x32_bf16 v[126:129], v[136:139], v[168:171], v[126:129]
	v_mfma_f32_16x16x32_bf16 v[122:125], v[144:147], v[168:171], v[122:125]
	v_mfma_f32_16x16x32_bf16 v[118:121], v[136:139], v[176:179], v[118:121]
	v_mfma_f32_16x16x32_bf16 v[114:117], v[144:147], v[176:179], v[114:117]
	v_mfma_f32_16x16x32_bf16 v[102:105], v[136:139], v[184:187], v[102:105]
	v_mfma_f32_16x16x32_bf16 v[98:101], v[144:147], v[184:187], v[98:101]
	v_mfma_f32_16x16x32_bf16 v[86:89], v[136:139], v[192:195], v[86:89]
	v_mfma_f32_16x16x32_bf16 v[82:85], v[144:147], v[192:195], v[82:85]
	v_mfma_f32_16x16x32_bf16 v[126:129], v[140:143], v[172:175], v[126:129]
	v_mfma_f32_16x16x32_bf16 v[122:125], v[148:151], v[172:175], v[122:125]
	v_mfma_f32_16x16x32_bf16 v[118:121], v[140:143], v[180:183], v[118:121]
	v_mfma_f32_16x16x32_bf16 v[114:117], v[148:151], v[180:183], v[114:117]
	v_mfma_f32_16x16x32_bf16 v[102:105], v[140:143], v[188:191], v[102:105]
	v_mfma_f32_16x16x32_bf16 v[98:101], v[148:151], v[188:191], v[98:101]
	v_mfma_f32_16x16x32_bf16 v[86:89], v[140:143], v[196:199], v[86:89]
	v_mfma_f32_16x16x32_bf16 v[82:85], v[148:151], v[196:199], v[82:85]
	v_mfma_f32_16x16x32_bf16 v[110:113], v[152:155], v[168:171], v[110:113]
	v_mfma_f32_16x16x32_bf16 v[106:109], v[160:163], v[168:171], v[106:109]
	v_mfma_f32_16x16x32_bf16 v[94:97], v[152:155], v[176:179], v[94:97]
	v_mfma_f32_16x16x32_bf16 v[90:93], v[160:163], v[176:179], v[90:93]
	v_mfma_f32_16x16x32_bf16 v[78:81], v[152:155], v[184:187], v[78:81]
	v_mfma_f32_16x16x32_bf16 v[74:77], v[160:163], v[184:187], v[74:77]
	v_mfma_f32_16x16x32_bf16 v[70:73], v[152:155], v[192:195], v[70:73]
	v_mfma_f32_16x16x32_bf16 v[66:69], v[160:163], v[192:195], v[66:69]
	v_mfma_f32_16x16x32_bf16 v[110:113], v[156:159], v[172:175], v[110:113]
	v_mfma_f32_16x16x32_bf16 v[106:109], v[164:167], v[172:175], v[106:109]
	v_mfma_f32_16x16x32_bf16 v[94:97], v[156:159], v[180:183], v[94:97]
	v_mfma_f32_16x16x32_bf16 v[90:93], v[164:167], v[180:183], v[90:93]
	v_mfma_f32_16x16x32_bf16 v[78:81], v[156:159], v[188:191], v[78:81]
	v_mfma_f32_16x16x32_bf16 v[74:77], v[164:167], v[188:191], v[74:77]
	v_mfma_f32_16x16x32_bf16 v[70:73], v[156:159], v[196:199], v[70:73]
	v_mfma_f32_16x16x32_bf16 v[66:69], v[164:167], v[196:199], v[66:69]
	s_barrier
	s_add_u32 s74, s16, 0x80
	s_addc_u32 s75, s17, 0
	v_mov_b32_e32 v0, v133
	s_mov_b32 m0, s40
	ds_read_b128 v[168:171], v135 offset:49152
	ds_read_b128 v[172:175], v135 offset:50176
	ds_read_b128 v[176:179], v135 offset:51200
	ds_read_b128 v[180:183], v135 offset:52224
	ds_read_b128 v[184:187], v135 offset:53248
	ds_read_b128 v[188:191], v135 offset:54272
	ds_read_b128 v[192:195], v135 offset:55296
	ds_read_b128 v[196:199], v135 offset:56320
	s_nop 0
	global_load_lds_dwordx4 v0, s[74:75]
	s_add_u32 s74, s16, 0x40080
	s_addc_u32 s75, s17, 0
	v_mov_b32_e32 v0, v133
	s_mov_b32 m0, s41
	s_nop 0
	global_load_lds_dwordx4 v0, s[74:75]
	s_add_u32 s74, s16, 0x80080
	s_addc_u32 s75, s17, 0
	v_mov_b32_e32 v0, v133
	s_mov_b32 m0, s48
	s_add_u32 s16, s16, 0xc0080
	global_load_lds_dwordx4 v0, s[74:75]
	s_addc_u32 s17, s17, 0
	v_mov_b32_e32 v0, v133
	s_mov_b32 m0, s50
	s_add_u32 s4, s4, 0x40080
	global_load_lds_dwordx4 v0, s[16:17]
	v_mov_b32_e32 v0, v132
	s_mov_b32 m0, s42
	s_addc_u32 s5, s5, 0
	global_load_lds_dwordx4 v0, s[6:7]
	v_mov_b32_e32 v0, v132
	s_mov_b32 m0, s43
	s_nop 0
	global_load_lds_dwordx4 v0, s[4:5]
	s_waitcnt vmcnt(8)
	s_waitcnt lgkmcnt(0)
	s_barrier
	v_mfma_f32_16x16x32_bf16 v[62:65], v[136:139], v[168:171], v[62:65]
	v_mfma_f32_16x16x32_bf16 v[58:61], v[144:147], v[168:171], v[58:61]
	v_mfma_f32_16x16x32_bf16 v[54:57], v[136:139], v[176:179], v[54:57]
	v_mfma_f32_16x16x32_bf16 v[50:53], v[144:147], v[176:179], v[50:53]
	v_mfma_f32_16x16x32_bf16 v[38:41], v[136:139], v[184:187], v[38:41]
	v_mfma_f32_16x16x32_bf16 v[34:37], v[144:147], v[184:187], v[34:37]
	v_mfma_f32_16x16x32_bf16 v[22:25], v[136:139], v[192:195], v[22:25]
	v_mfma_f32_16x16x32_bf16 v[18:21], v[144:147], v[192:195], v[18:21]
	v_mfma_f32_16x16x32_bf16 v[62:65], v[140:143], v[172:175], v[62:65]
	v_mfma_f32_16x16x32_bf16 v[58:61], v[148:151], v[172:175], v[58:61]
	v_mfma_f32_16x16x32_bf16 v[54:57], v[140:143], v[180:183], v[54:57]
	v_mfma_f32_16x16x32_bf16 v[50:53], v[148:151], v[180:183], v[50:53]
	v_mfma_f32_16x16x32_bf16 v[38:41], v[140:143], v[188:191], v[38:41]
	v_mfma_f32_16x16x32_bf16 v[34:37], v[148:151], v[188:191], v[34:37]
	v_mfma_f32_16x16x32_bf16 v[22:25], v[140:143], v[196:199], v[22:25]
	v_mfma_f32_16x16x32_bf16 v[18:21], v[148:151], v[196:199], v[18:21]
	v_mfma_f32_16x16x32_bf16 v[46:49], v[152:155], v[168:171], v[46:49]
	v_mfma_f32_16x16x32_bf16 v[42:45], v[160:163], v[168:171], v[42:45]
	v_mfma_f32_16x16x32_bf16 v[30:33], v[152:155], v[176:179], v[30:33]
	v_mfma_f32_16x16x32_bf16 v[26:29], v[160:163], v[176:179], v[26:29]
	v_mfma_f32_16x16x32_bf16 v[14:17], v[152:155], v[184:187], v[14:17]
	v_mfma_f32_16x16x32_bf16 v[10:13], v[160:163], v[184:187], v[10:13]
	v_mfma_f32_16x16x32_bf16 v[6:9], v[152:155], v[192:195], v[6:9]
	v_mfma_f32_16x16x32_bf16 v[2:5], v[160:163], v[192:195], v[2:5]
	v_mfma_f32_16x16x32_bf16 v[46:49], v[156:159], v[172:175], v[46:49]
	v_mfma_f32_16x16x32_bf16 v[42:45], v[164:167], v[172:175], v[42:45]
	v_mfma_f32_16x16x32_bf16 v[30:33], v[156:159], v[180:183], v[30:33]
	v_mfma_f32_16x16x32_bf16 v[26:29], v[164:167], v[180:183], v[26:29]
	v_mfma_f32_16x16x32_bf16 v[14:17], v[156:159], v[188:191], v[14:17]
	v_mfma_f32_16x16x32_bf16 v[10:13], v[164:167], v[188:191], v[10:13]
	v_mfma_f32_16x16x32_bf16 v[6:9], v[156:159], v[196:199], v[6:9]
	v_mfma_f32_16x16x32_bf16 v[2:5], v[164:167], v[196:199], v[2:5]
	s_barrier
	s_add_i32 s72, s72, 2
	s_add_u32 s64, s64, 0x100
	s_addc_u32 s66, s66, 0
	s_add_u32 s68, s68, 0x100
	s_addc_u32 s70, s70, 0
	s_cmp_gt_u32 s72, 29
	s_cbranch_scc0 .LBB0_1046

.LBB0_1653:
	s_ashr_i32 s15, s14, 31
	s_lshl_b64 s[18:19], s[14:15], 20
	s_add_u32 s18, s88, s18
	s_addc_u32 s19, s89, s19
	s_and_b64 s[20:21], s[4:5], exec
	s_cselect_b32 s15, s19, s17
	s_cselect_b32 s58, s18, s16
	s_ashr_i32 s13, s12, 31
	s_lshl_b64 s[20:21], s[12:13], 20
	s_add_u32 s20, s24, s20
	s_addc_u32 s21, s25, s21
	s_and_b64 s[22:23], s[4:5], exec
	s_cselect_b32 s13, s21, s7
	s_cselect_b32 s60, s20, s6
	s_add_u32 s62, s16, 0x100
	s_addc_u32 s64, s17, 0
	s_add_u32 s66, s6, 0x100
	s_addc_u32 s68, s7, 0
	s_mov_b32 s70, -2
	v_add_u32_e32 v130, 0x10000, v133
	ds_read_b128 v[136:139], v130
	ds_read_b128 v[140:143], v130 offset:1024
	ds_read_b128 v[144:147], v130 offset:2048
	ds_read_b128 v[148:151], v130 offset:3072
	v_add_u32_e32 v130, 0x14000, v133
	ds_read_b128 v[152:155], v130
	ds_read_b128 v[156:159], v130 offset:1024
	ds_read_b128 v[160:163], v130 offset:2048
	ds_read_b128 v[164:167], v130 offset:3072
	s_cmp_eq_u32 s70, 28
	s_cselect_b32 s6, s58, s62
	s_cselect_b32 s7, s15, s64
	s_cselect_b32 s22, s60, s66
	s_cselect_b32 s23, s13, s68
	s_add_u32 s16, s6, 0x80
	s_addc_u32 s17, s7, 0
	s_add_u32 s74, s62, 0x7ff80
	s_addc_u32 s75, s64, 0
	v_mov_b32_e32 v130, v0
	ds_read_b128 v[168:171], v134
	ds_read_b128 v[172:175], v134 offset:1024
	ds_read_b128 v[176:179], v134 offset:2048
	ds_read_b128 v[180:183], v134 offset:3072
	ds_read_b128 v[184:187], v134 offset:4096
	ds_read_b128 v[188:191], v134 offset:5120
	ds_read_b128 v[192:195], v134 offset:6144
	ds_read_b128 v[196:199], v134 offset:7168
	s_add_i32 m0, s26, 0xc000
	s_nop 0
	global_load_lds_dwordx4 v130, s[74:75]
	s_add_u32 s74, s62, 0xbff80
	s_addc_u32 s75, s64, 0
	v_mov_b32_e32 v130, v0
	s_add_i32 m0, s26, 0xe000
	s_nop 0
	global_load_lds_dwordx4 v130, s[74:75]
	s_waitcnt vmcnt(8)
	s_waitcnt lgkmcnt(0)
	s_barrier
	v_mfma_f32_16x16x32_bf16 v[122:125], v[136:139], v[168:171], 0
	v_mfma_f32_16x16x32_bf16 v[114:117], v[144:147], v[168:171], 0
	v_mfma_f32_16x16x32_bf16 v[106:109], v[136:139], v[176:179], 0
	v_mfma_f32_16x16x32_bf16 v[98:101], v[144:147], v[176:179], 0
	v_mfma_f32_16x16x32_bf16 v[90:93], v[136:139], v[184:187], 0
	v_mfma_f32_16x16x32_bf16 v[82:85], v[144:147], v[184:187], 0
	v_mfma_f32_16x16x32_bf16 v[74:77], v[136:139], v[192:195], 0
	v_mfma_f32_16x16x32_bf16 v[66:69], v[144:147], v[192:195], 0
	v_mfma_f32_16x16x32_bf16 v[122:125], v[140:143], v[172:175], v[122:125]
	v_mfma_f32_16x16x32_bf16 v[114:117], v[148:151], v[172:175], v[114:117]
	v_mfma_f32_16x16x32_bf16 v[106:109], v[140:143], v[180:183], v[106:109]
	v_mfma_f32_16x16x32_bf16 v[98:101], v[148:151], v[180:183], v[98:101]
	v_mfma_f32_16x16x32_bf16 v[90:93], v[140:143], v[188:191], v[90:93]
	v_mfma_f32_16x16x32_bf16 v[82:85], v[148:151], v[188:191], v[82:85]
	v_mfma_f32_16x16x32_bf16 v[74:77], v[140:143], v[196:199], v[74:77]
	v_mfma_f32_16x16x32_bf16 v[66:69], v[148:151], v[196:199], v[66:69]
	v_mfma_f32_16x16x32_bf16 v[126:129], v[152:155], v[168:171], 0
	v_mfma_f32_16x16x32_bf16 v[118:121], v[160:163], v[168:171], 0
	v_mfma_f32_16x16x32_bf16 v[110:113], v[152:155], v[176:179], 0
	v_mfma_f32_16x16x32_bf16 v[102:105], v[160:163], v[176:179], 0
	v_mfma_f32_16x16x32_bf16 v[94:97], v[152:155], v[184:187], 0
	v_mfma_f32_16x16x32_bf16 v[86:89], v[160:163], v[184:187], 0
	v_mfma_f32_16x16x32_bf16 v[78:81], v[152:155], v[192:195], 0
	v_mfma_f32_16x16x32_bf16 v[70:73], v[160:163], v[192:195], 0
	v_mfma_f32_16x16x32_bf16 v[126:129], v[156:159], v[172:175], v[126:129]
	v_mfma_f32_16x16x32_bf16 v[118:121], v[164:167], v[172:175], v[118:121]
	v_mfma_f32_16x16x32_bf16 v[110:113], v[156:159], v[180:183], v[110:113]
	v_mfma_f32_16x16x32_bf16 v[102:105], v[164:167], v[180:183], v[102:105]
	v_mfma_f32_16x16x32_bf16 v[94:97], v[156:159], v[188:191], v[94:97]
	v_mfma_f32_16x16x32_bf16 v[86:89], v[164:167], v[188:191], v[86:89]
	v_mfma_f32_16x16x32_bf16 v[78:81], v[156:159], v[196:199], v[78:81]
	v_mfma_f32_16x16x32_bf16 v[70:73], v[164:167], v[196:199], v[70:73]
	s_barrier
	s_mov_b64 s[74:75], s[22:23]
	v_mov_b32_e32 v130, v132
	s_mov_b32 m0, s27
	ds_read_b128 v[168:171], v134 offset:16384
	ds_read_b128 v[172:175], v134 offset:17408
	ds_read_b128 v[176:179], v134 offset:18432
	ds_read_b128 v[180:183], v134 offset:19456
	ds_read_b128 v[184:187], v134 offset:20480
	ds_read_b128 v[188:191], v134 offset:21504
	ds_read_b128 v[192:195], v134 offset:22528
	ds_read_b128 v[196:199], v134 offset:23552
	s_nop 0
	global_load_lds_dwordx4 v130, s[74:75]
	s_add_u32 s74, s22, 0x40000
	s_addc_u32 s75, s23, 0
	v_mov_b32_e32 v130, v132
	s_mov_b32 m0, s28
	s_nop 0
	global_load_lds_dwordx4 v130, s[74:75]
	s_add_u32 s74, s22, 0x80000
	s_addc_u32 s75, s23, 0
	v_mov_b32_e32 v130, v132
	s_mov_b32 m0, s29
	s_nop 0
	global_load_lds_dwordx4 v130, s[74:75]
	s_add_u32 s74, s22, 0xc0000
	s_addc_u32 s75, s23, 0
	v_mov_b32_e32 v130, v132
	s_mov_b32 m0, s30
	s_nop 0
	global_load_lds_dwordx4 v130, s[74:75]
	s_mov_b64 s[74:75], s[6:7]
	v_mov_b32_e32 v130, v0
	s_mov_b32 m0, s26
	s_nop 0
	global_load_lds_dwordx4 v130, s[74:75]
	s_add_u32 s74, s6, 0x40000
	s_addc_u32 s75, s7, 0
	v_mov_b32_e32 v130, v0
	s_mov_b32 m0, s31
	s_nop 0
	global_load_lds_dwordx4 v130, s[74:75]
	s_waitcnt vmcnt(8)
	s_waitcnt lgkmcnt(0)
	s_barrier
	v_mfma_f32_16x16x32_bf16 v[58:61], v[136:139], v[168:171], 0
	v_mfma_f32_16x16x32_bf16 v[50:53], v[144:147], v[168:171], 0
	v_mfma_f32_16x16x32_bf16 v[42:45], v[136:139], v[176:179], 0
	v_mfma_f32_16x16x32_bf16 v[34:37], v[144:147], v[176:179], 0
	v_mfma_f32_16x16x32_bf16 v[26:29], v[136:139], v[184:187], 0
	v_mfma_f32_16x16x32_bf16 v[18:21], v[144:147], v[184:187], 0
	v_mfma_f32_16x16x32_bf16 v[10:13], v[136:139], v[192:195], 0
	v_mfma_f32_16x16x32_bf16 v[2:5], v[144:147], v[192:195], 0
	v_mfma_f32_16x16x32_bf16 v[58:61], v[140:143], v[172:175], v[58:61]
	v_mfma_f32_16x16x32_bf16 v[50:53], v[148:151], v[172:175], v[50:53]
	v_mfma_f32_16x16x32_bf16 v[42:45], v[140:143], v[180:183], v[42:45]
	v_mfma_f32_16x16x32_bf16 v[34:37], v[148:151], v[180:183], v[34:37]
	v_mfma_f32_16x16x32_bf16 v[26:29], v[140:143], v[188:191], v[26:29]
	v_mfma_f32_16x16x32_bf16 v[18:21], v[148:151], v[188:191], v[18:21]
	v_mfma_f32_16x16x32_bf16 v[10:13], v[140:143], v[196:199], v[10:13]
	v_mfma_f32_16x16x32_bf16 v[2:5], v[148:151], v[196:199], v[2:5]
	v_mfma_f32_16x16x32_bf16 v[62:65], v[152:155], v[168:171], 0
	v_mfma_f32_16x16x32_bf16 v[54:57], v[160:163], v[168:171], 0
	v_mfma_f32_16x16x32_bf16 v[46:49], v[152:155], v[176:179], 0
	v_mfma_f32_16x16x32_bf16 v[38:41], v[160:163], v[176:179], 0
	v_mfma_f32_16x16x32_bf16 v[30:33], v[152:155], v[184:187], 0
	v_mfma_f32_16x16x32_bf16 v[22:25], v[160:163], v[184:187], 0
	v_mfma_f32_16x16x32_bf16 v[14:17], v[152:155], v[192:195], 0
	v_mfma_f32_16x16x32_bf16 v[6:9], v[160:163], v[192:195], 0
	v_mfma_f32_16x16x32_bf16 v[62:65], v[156:159], v[172:175], v[62:65]
	v_mfma_f32_16x16x32_bf16 v[54:57], v[164:167], v[172:175], v[54:57]
	v_mfma_f32_16x16x32_bf16 v[46:49], v[156:159], v[180:183], v[46:49]
	v_mfma_f32_16x16x32_bf16 v[38:41], v[164:167], v[180:183], v[38:41]
	v_mfma_f32_16x16x32_bf16 v[30:33], v[156:159], v[188:191], v[30:33]
	v_mfma_f32_16x16x32_bf16 v[22:25], v[164:167], v[188:191], v[22:25]
	v_mfma_f32_16x16x32_bf16 v[14:17], v[156:159], v[196:199], v[14:17]
	v_mfma_f32_16x16x32_bf16 v[6:9], v[164:167], v[196:199], v[6:9]
	s_barrier
	v_add_u32_e32 v130, 0x18000, v133
	ds_read_b128 v[136:139], v130
	ds_read_b128 v[140:143], v130 offset:1024
	ds_read_b128 v[144:147], v130 offset:2048
	ds_read_b128 v[148:151], v130 offset:3072
	v_add_u32_e32 v130, 0x1c000, v133
	ds_read_b128 v[152:155], v130
	ds_read_b128 v[156:159], v130 offset:1024
	ds_read_b128 v[160:163], v130 offset:2048
	ds_read_b128 v[164:167], v130 offset:3072
	s_add_u32 s74, s6, 0x80000
	s_addc_u32 s75, s7, 0
	v_mov_b32_e32 v130, v0
	s_mov_b32 m0, s34
	ds_read_b128 v[168:171], v134 offset:32768
	ds_read_b128 v[172:175], v134 offset:33792
	ds_read_b128 v[176:179], v134 offset:34816
	ds_read_b128 v[180:183], v134 offset:35840
	ds_read_b128 v[184:187], v134 offset:36864
	ds_read_b128 v[188:191], v134 offset:37888
	ds_read_b128 v[192:195], v134 offset:38912
	ds_read_b128 v[196:199], v134 offset:39936
	s_nop 0
	global_load_lds_dwordx4 v130, s[74:75]
	s_add_u32 s74, s6, 0xc0000
	s_addc_u32 s75, s7, 0
	v_mov_b32_e32 v130, v0
	s_mov_b32 m0, s35
	s_nop 0
	global_load_lds_dwordx4 v130, s[74:75]
	s_waitcnt vmcnt(8)
	s_waitcnt lgkmcnt(0)
	s_barrier
	v_mfma_f32_16x16x32_bf16 v[122:125], v[136:139], v[168:171], v[122:125]
	v_mfma_f32_16x16x32_bf16 v[114:117], v[144:147], v[168:171], v[114:117]
	v_mfma_f32_16x16x32_bf16 v[106:109], v[136:139], v[176:179], v[106:109]
	v_mfma_f32_16x16x32_bf16 v[98:101], v[144:147], v[176:179], v[98:101]
	v_mfma_f32_16x16x32_bf16 v[90:93], v[136:139], v[184:187], v[90:93]
	v_mfma_f32_16x16x32_bf16 v[82:85], v[144:147], v[184:187], v[82:85]
	v_mfma_f32_16x16x32_bf16 v[74:77], v[136:139], v[192:195], v[74:77]
	v_mfma_f32_16x16x32_bf16 v[66:69], v[144:147], v[192:195], v[66:69]
	v_mfma_f32_16x16x32_bf16 v[122:125], v[140:143], v[172:175], v[122:125]
	v_mfma_f32_16x16x32_bf16 v[114:117], v[148:151], v[172:175], v[114:117]
	v_mfma_f32_16x16x32_bf16 v[106:109], v[140:143], v[180:183], v[106:109]
	v_mfma_f32_16x16x32_bf16 v[98:101], v[148:151], v[180:183], v[98:101]
	v_mfma_f32_16x16x32_bf16 v[90:93], v[140:143], v[188:191], v[90:93]
	v_mfma_f32_16x16x32_bf16 v[82:85], v[148:151], v[188:191], v[82:85]
	v_mfma_f32_16x16x32_bf16 v[74:77], v[140:143], v[196:199], v[74:77]
	v_mfma_f32_16x16x32_bf16 v[66:69], v[148:151], v[196:199], v[66:69]
	v_mfma_f32_16x16x32_bf16 v[126:129], v[152:155], v[168:171], v[126:129]
	v_mfma_f32_16x16x32_bf16 v[118:121], v[160:163], v[168:171], v[118:121]
	v_mfma_f32_16x16x32_bf16 v[110:113], v[152:155], v[176:179], v[110:113]
	v_mfma_f32_16x16x32_bf16 v[102:105], v[160:163], v[176:179], v[102:105]
	v_mfma_f32_16x16x32_bf16 v[94:97], v[152:155], v[184:187], v[94:97]
	v_mfma_f32_16x16x32_bf16 v[86:89], v[160:163], v[184:187], v[86:89]
	v_mfma_f32_16x16x32_bf16 v[78:81], v[152:155], v[192:195], v[78:81]
	v_mfma_f32_16x16x32_bf16 v[70:73], v[160:163], v[192:195], v[70:73]
	v_mfma_f32_16x16x32_bf16 v[126:129], v[156:159], v[172:175], v[126:129]
	v_mfma_f32_16x16x32_bf16 v[118:121], v[164:167], v[172:175], v[118:121]
	v_mfma_f32_16x16x32_bf16 v[110:113], v[156:159], v[180:183], v[110:113]
	v_mfma_f32_16x16x32_bf16 v[102:105], v[164:167], v[180:183], v[102:105]
	v_mfma_f32_16x16x32_bf16 v[94:97], v[156:159], v[188:191], v[94:97]
	v_mfma_f32_16x16x32_bf16 v[86:89], v[164:167], v[188:191], v[86:89]
	v_mfma_f32_16x16x32_bf16 v[78:81], v[156:159], v[196:199], v[78:81]
	v_mfma_f32_16x16x32_bf16 v[70:73], v[164:167], v[196:199], v[70:73]
	s_barrier
	s_add_u32 s74, s22, 0x80
	s_addc_u32 s75, s23, 0
	v_mov_b32_e32 v130, v132
	s_mov_b32 m0, s38
	ds_read_b128 v[168:171], v134 offset:49152
	ds_read_b128 v[172:175], v134 offset:50176
	ds_read_b128 v[176:179], v134 offset:51200
	ds_read_b128 v[180:183], v134 offset:52224
	ds_read_b128 v[184:187], v134 offset:53248
	ds_read_b128 v[188:191], v134 offset:54272
	ds_read_b128 v[192:195], v134 offset:55296
	ds_read_b128 v[196:199], v134 offset:56320
	s_nop 0
	global_load_lds_dwordx4 v130, s[74:75]
	s_add_u32 s74, s22, 0x40080
	s_addc_u32 s75, s23, 0
	v_mov_b32_e32 v130, v132
	s_mov_b32 m0, s39
	s_nop 0
	global_load_lds_dwordx4 v130, s[74:75]
	s_add_u32 s74, s22, 0x80080
	s_addc_u32 s75, s23, 0
	v_mov_b32_e32 v130, v132
	s_mov_b32 m0, s43
	s_add_u32 s22, s22, 0xc0080
	global_load_lds_dwordx4 v130, s[74:75]
	s_addc_u32 s23, s23, 0
	v_mov_b32_e32 v130, v132
	s_mov_b32 m0, s48
	s_add_u32 s6, s6, 0x40080
	global_load_lds_dwordx4 v130, s[22:23]
	v_mov_b32_e32 v130, v0
	s_mov_b32 m0, s41
	s_addc_u32 s7, s7, 0
	global_load_lds_dwordx4 v130, s[16:17]
	v_mov_b32_e32 v130, v0
	s_mov_b32 m0, s42
	s_nop 0
	global_load_lds_dwordx4 v130, s[6:7]
	s_waitcnt vmcnt(8)
	s_waitcnt lgkmcnt(0)
	s_barrier
	v_mfma_f32_16x16x32_bf16 v[58:61], v[136:139], v[168:171], v[58:61]
	v_mfma_f32_16x16x32_bf16 v[50:53], v[144:147], v[168:171], v[50:53]
	v_mfma_f32_16x16x32_bf16 v[42:45], v[136:139], v[176:179], v[42:45]
	v_mfma_f32_16x16x32_bf16 v[34:37], v[144:147], v[176:179], v[34:37]
	v_mfma_f32_16x16x32_bf16 v[26:29], v[136:139], v[184:187], v[26:29]
	v_mfma_f32_16x16x32_bf16 v[18:21], v[144:147], v[184:187], v[18:21]
	v_mfma_f32_16x16x32_bf16 v[10:13], v[136:139], v[192:195], v[10:13]
	v_mfma_f32_16x16x32_bf16 v[2:5], v[144:147], v[192:195], v[2:5]
	v_mfma_f32_16x16x32_bf16 v[58:61], v[140:143], v[172:175], v[58:61]
	v_mfma_f32_16x16x32_bf16 v[50:53], v[148:151], v[172:175], v[50:53]
	v_mfma_f32_16x16x32_bf16 v[42:45], v[140:143], v[180:183], v[42:45]
	v_mfma_f32_16x16x32_bf16 v[34:37], v[148:151], v[180:183], v[34:37]
	v_mfma_f32_16x16x32_bf16 v[26:29], v[140:143], v[188:191], v[26:29]
	v_mfma_f32_16x16x32_bf16 v[18:21], v[148:151], v[188:191], v[18:21]
	v_mfma_f32_16x16x32_bf16 v[10:13], v[140:143], v[196:199], v[10:13]
	v_mfma_f32_16x16x32_bf16 v[2:5], v[148:151], v[196:199], v[2:5]
	v_mfma_f32_16x16x32_bf16 v[62:65], v[152:155], v[168:171], v[62:65]
	v_mfma_f32_16x16x32_bf16 v[54:57], v[160:163], v[168:171], v[54:57]
	v_mfma_f32_16x16x32_bf16 v[46:49], v[152:155], v[176:179], v[46:49]
	v_mfma_f32_16x16x32_bf16 v[38:41], v[160:163], v[176:179], v[38:41]
	v_mfma_f32_16x16x32_bf16 v[30:33], v[152:155], v[184:187], v[30:33]
	v_mfma_f32_16x16x32_bf16 v[22:25], v[160:163], v[184:187], v[22:25]
	v_mfma_f32_16x16x32_bf16 v[14:17], v[152:155], v[192:195], v[14:17]
	v_mfma_f32_16x16x32_bf16 v[6:9], v[160:163], v[192:195], v[6:9]
	v_mfma_f32_16x16x32_bf16 v[62:65], v[156:159], v[172:175], v[62:65]
	v_mfma_f32_16x16x32_bf16 v[54:57], v[164:167], v[172:175], v[54:57]
	v_mfma_f32_16x16x32_bf16 v[46:49], v[156:159], v[180:183], v[46:49]
	v_mfma_f32_16x16x32_bf16 v[38:41], v[164:167], v[180:183], v[38:41]
	v_mfma_f32_16x16x32_bf16 v[30:33], v[156:159], v[188:191], v[30:33]
	v_mfma_f32_16x16x32_bf16 v[22:25], v[164:167], v[188:191], v[22:25]
	v_mfma_f32_16x16x32_bf16 v[14:17], v[156:159], v[196:199], v[14:17]
	v_mfma_f32_16x16x32_bf16 v[6:9], v[164:167], v[196:199], v[6:9]
	s_barrier
	s_add_i32 s70, s70, 2
	s_add_u32 s62, s62, 0x100
	s_addc_u32 s64, s64, 0
	s_add_u32 s66, s66, 0x100
	s_addc_u32 s68, s68, 0
	s_cmp_gt_u32 s70, 29
	s_cbranch_scc0 .LBB0_1654
